# S5 task preamble: 16 wide throw-away loads warm the 16 KB of b_re/b_im/c_re/c_im fragment data before the 12-step load/wait ladder (on top of the hand-off trim)
# baseline (speedup 1.0000x reference)
; __device__ __forceinline__ void sincos_acc(float th, float& s, float& c) {
;     const double t = (double)th; const double k = rint(t * 0.15915494309189535); const double r = fma(-k, 6.283185307179586, t);
;     const double r2 = r * r; double ts = r, ss = r, tc = 1.0, cs = 1.0;
; #pragma unroll
;     for (int n = 1; n <= 14; ++n) { ts *= -r2 * (1.0 / (double)((2 * n) * (2 * n + 1))); ss += ts; tc *= -r2 * (1.0 / (double)((2 * n - 1) * (2 * n))); cs += tc; }
;     s = (float)ss; c = (float)cs;
; __device__ __forceinline__ void s5_phase(LAS unsigned char* lds, CParams* pp, int layer, int G, int c) {
;     ...
;     for (int task = c; task < 256; task += G) {
;         const int b = task >> 5, g = (task & 31) * 4 + gl;
;         const size_t pg = ((size_t)(layer * 2 + dir) * 128 + g);
;         const float are = pp->in[4][pg * 64 + lane], aim = pp->in[5][pg * 64 + lane];
;         const float dt = expf(pp->in[6][pg]);
;         float sn, cs; sincos_acc(aim * dt, sn, cs);
;         const float mag = expf(are * dt); const float lbr = mag * cs, lbi = mag * sn;
.LBB0_345:
	s_load_dwordx8 s[60:67], s[0:1], 0x38
	s_lshl_b32 s98, s2, 2
	s_and_b32 s98, s98, 0x7c
	s_or_b32 s98, s98, s9
	s_or_b32 s98, s98, s84
	s_lshl_b32 s98, s98, 12
	v_lshlrev_b32_e32 v0, 4, v70
	s_waitcnt lgkmcnt(0)
	s_add_u32 s100, s60, s98
	s_addc_u32 s101, s61, 0
	global_load_dwordx4 v[210:213], v0, s[100:101]
	global_load_dwordx4 v[214:217], v0, s[100:101] offset:1024
	global_load_dwordx4 v[218:221], v0, s[100:101] offset:2048
	global_load_dwordx4 v[222:225], v0, s[100:101] offset:3072
	s_add_u32 s100, s62, s98
	s_addc_u32 s101, s63, 0
	global_load_dwordx4 v[226:229], v0, s[100:101]
	global_load_dwordx4 v[230:233], v0, s[100:101] offset:1024
	global_load_dwordx4 v[234:237], v0, s[100:101] offset:2048
	global_load_dwordx4 v[210:213], v0, s[100:101] offset:3072
	s_add_u32 s100, s64, s98
	s_addc_u32 s101, s65, 0
	global_load_dwordx4 v[214:217], v0, s[100:101]
	global_load_dwordx4 v[218:221], v0, s[100:101] offset:1024
	global_load_dwordx4 v[222:225], v0, s[100:101] offset:2048
	global_load_dwordx4 v[226:229], v0, s[100:101] offset:3072
	s_add_u32 s100, s66, s98
	s_addc_u32 s101, s67, 0
	global_load_dwordx4 v[230:233], v0, s[100:101]
	global_load_dwordx4 v[234:237], v0, s[100:101] offset:1024
	global_load_dwordx4 v[210:213], v0, s[100:101] offset:2048
	global_load_dwordx4 v[214:217], v0, s[100:101] offset:3072
	s_lshl_b32 s4, s2, 2
	s_and_b32 s4, s4, 0x7c
	s_or_b32 s4, s4, s9
	s_load_dwordx4 s[60:63], s[0:1], 0x20
	s_or_b32 s64, s84, s4
	s_mov_b32 s65, s85
	s_lshl_b64 s[66:67], s[64:65], 6
	v_mov_b32_e32 v1, s67
	v_or_b32_e32 v0, s66, v70
	s_lshl_b64 s[28:29], s[64:65], 2
	v_lshlrev_b64 v[0:1], 2, v[0:1]
	s_add_u32 s28, s86, s28
	s_waitcnt lgkmcnt(0)
	v_lshl_add_u64 v[2:3], s[60:61], 0, v[0:1]
	v_lshl_add_u64 v[0:1], s[62:63], 0, v[0:1]
	s_addc_u32 s29, s87, s29
	global_load_dword v7, v[0:1], off
	global_load_dword v6, v[2:3], off
	s_mov_b32 s5, 0x3fb8aa3b
	global_load_dword v0, v179, s[28:29]
	s_mov_b32 s36, 0xc2ce8ed0
	s_mov_b32 s88, 0x42b17218
	s_mov_b32 s28, 0x6dc9c883
	s_mov_b32 s29, 0x3fc45f30
	s_mov_b32 s60, 0x9999999a
	s_mov_b32 s61, 0x3fa99999
	s_mov_b32 s62, 0x16816817
	s_mov_b32 s63, 0x3f768168
	v_lshlrev_b32_e32 v178, 2, v74
	s_waitcnt vmcnt(0)
	v_mul_f32_e32 v1, 0x3fb8aa3b, v0
	v_fma_f32 v2, v0, s5, -v1
	v_rndne_f32_e32 v3, v1
	v_fmac_f32_e32 v2, 0x32a5705f, v0
	v_sub_f32_e32 v1, v1, v3
	v_add_f32_e32 v1, v1, v2
	v_exp_f32_e32 v1, v1
	v_cvt_i32_f32_e32 v2, v3
	v_cmp_ngt_f32_e32 vcc, s36, v0
	v_ldexp_f32 v1, v1, v2
	s_nop 0
	v_cndmask_b32_e32 v1, 0, v1, vcc
	v_cmp_nlt_f32_e32 vcc, s88, v0
	s_nop 1
	v_cndmask_b32_e32 v8, v205, v1, vcc
	v_mul_f32_e32 v0, v7, v8
	v_cvt_f64_f32_e32 v[0:1], v0
	v_mul_f64 v[2:3], v[0:1], s[28:29]
	s_mov_b32 s28, 0x54442d18
	v_rndne_f64_e32 v[2:3], v[2:3]
	s_mov_b32 s29, 0xc01921fb
	v_fmac_f64_e32 v[0:1], s[28:29], v[2:3]
	v_mul_f64 v[2:3], v[0:1], -v[0:1]
	s_mov_b32 s28, 0x55555555
	s_mov_b32 s29, 0x3fc55555
	v_mul_f64 v[14:15], v[2:3], s[60:61]
	v_readlane_b32 s60, v238, 17
	v_mul_f64 v[4:5], v[2:3], s[28:29]
	v_readlane_b32 s61, v238, 18
	v_mul_f64 v[10:11], v[0:1], v[4:5]
	v_fmac_f64_e32 v[0:1], v[0:1], v[4:5]
	s_mov_b32 s29, s61
	v_mul_f64 v[16:17], v[14:15], v[10:11]
	v_fmac_f64_e32 v[0:1], v[14:15], v[10:11]
	v_mul_f64 v[10:11], v[2:3], s[28:29]
	s_mov_b32 s28, 0x18618618
	v_mul_f64 v[12:13], v[2:3], 0.5
	v_fma_f64 v[4:5], v[2:3], 0.5, 1.0
	s_mov_b32 s29, 0x3f986186
	v_writelane_b32 v238, s60, 17
	v_mul_f64 v[14:15], v[12:13], v[10:11]
	v_fmac_f64_e32 v[4:5], v[12:13], v[10:11]
	v_mul_f64 v[10:11], v[2:3], s[28:29]
	s_mov_b32 s28, 0x11111111
	v_writelane_b32 v238, s61, 18
	s_mov_b32 s29, 0x3fa11111
	s_mov_b32 s60, 0x1c71c71c
	v_mul_f64 v[12:13], v[10:11], v[16:17]
	v_fmac_f64_e32 v[0:1], v[10:11], v[16:17]
	v_mul_f64 v[10:11], v[2:3], s[28:29]
	s_mov_b32 s61, 0x3f8c71c7
	v_mul_f64 v[16:17], v[10:11], v[14:15]
	v_fmac_f64_e32 v[4:5], v[10:11], v[14:15]
	v_mul_f64 v[10:11], v[2:3], s[60:61]
	s_mov_b32 s60, 0x92492492
	s_mov_b32 s61, 0x3f924924
	v_mul_f64 v[14:15], v[10:11], v[12:13]
	v_fmac_f64_e32 v[0:1], v[10:11], v[12:13]
	v_mul_f64 v[10:11], v[2:3], s[60:61]
	s_mov_b32 s60, 0x29e4129e
	s_mov_b32 s61, 0x3f829e41
	v_mul_f64 v[12:13], v[10:11], v[16:17]
	v_fmac_f64_e32 v[4:5], v[10:11], v[16:17]
	v_mul_f64 v[10:11], v[2:3], s[60:61]
	s_mov_b32 s60, 0x16c16c17
	s_mov_b32 s61, 0x3f86c16c
	v_mul_f64 v[16:17], v[10:11], v[14:15]
	v_fmac_f64_e32 v[0:1], v[10:11], v[14:15]
	v_mul_f64 v[10:11], v[2:3], s[60:61]
	s_mov_b32 s60, 0x1a41a41a
	s_mov_b32 s61, 0x3f7a41a4
	v_mul_f64 v[14:15], v[10:11], v[12:13]
	v_fmac_f64_e32 v[4:5], v[10:11], v[12:13]
	v_mul_f64 v[10:11], v[2:3], s[60:61]
	s_mov_b32 s60, 0xf07c1f08
	s_mov_b32 s61, 0x3f7f07c1
	v_mul_f64 v[12:13], v[10:11], v[16:17]
	v_fmac_f64_e32 v[0:1], v[10:11], v[16:17]
	v_mul_f64 v[10:11], v[2:3], s[60:61]
	s_mov_b32 s60, 0x13813814
	s_mov_b32 s61, 0x3f738138
	v_mul_f64 v[16:17], v[10:11], v[14:15]
	v_fmac_f64_e32 v[4:5], v[10:11], v[14:15]
	v_mul_f64 v[10:11], v[2:3], s[60:61]
	v_mul_f64 v[14:15], v[10:11], v[12:13]
	v_fmac_f64_e32 v[0:1], v[10:11], v[12:13]
	v_mul_f64 v[10:11], v[2:3], s[62:63]
	s_mov_b32 s62, 0x1e1e1e1e
	s_mov_b32 s63, 0x3f6e1e1e
	v_mul_f64 v[12:13], v[10:11], v[16:17]
	v_fmac_f64_e32 v[4:5], v[10:11], v[16:17]
	v_mul_f64 v[10:11], v[2:3], s[62:63]
	v_readlane_b32 s62, v238, 19
	v_readlane_b32 s63, v238, 20
	s_mov_b32 s29, s63
	v_mul_f64 v[16:17], v[10:11], v[14:15]
	v_fmac_f64_e32 v[0:1], v[10:11], v[14:15]
	v_mul_f64 v[10:11], v[2:3], s[28:29]
	s_mov_b32 s28, 0xfd017f40
	s_mov_b32 s61, s63
	s_mov_b32 s29, 0x3f67f405
	v_writelane_b32 v238, s60, 19
	v_mul_f64 v[14:15], v[10:11], v[12:13]
; __device__ __forceinline__ unsigned cvt_pk_bf16(float lo, float hi) { f32x2_t v = {lo, hi}; bf16x2_t b = __builtin_convertvector(v, bf16x2_t); return __builtin_bit_cast(unsigned, b); }
; __device__ __forceinline__ void sincos_acc(float th, float& s, float& c) {
;     const double t = (double)th; const double k = rint(t * 0.15915494309189535); const double r = fma(-k, 6.283185307179586, t);
;     const double r2 = r * r; double ts = r, ss = r, tc = 1.0, cs = 1.0;
; #pragma unroll
;     for (int n = 1; n <= 14; ++n) { ts *= -r2 * (1.0 / (double)((2 * n) * (2 * n + 1))); ss += ts; tc *= -r2 * (1.0 / (double)((2 * n - 1) * (2 * n))); cs += tc; }
;     s = (float)ss; c = (float)cs;
; __device__ __forceinline__ void s5_phase(LAS unsigned char* lds, CParams* pp, int layer, int G, int c) {
;     ...
;         const float mag = expf(are * dt); const float lbr = mag * cs, lbi = mag * sn;
;         const float den = 1.0f / (are * are + aim * aim); const float xr_ = lbr - 1.0f, xi_ = lbi;
;         const float cfr = (xr_ * are + xi_ * aim) * den, cfi = (xi_ * are - xr_ * aim) * den;
;         bf16x8 Bf[8];
; #pragma unroll
;         for (int cb = 0; cb < 8; ++cb) { const int pb = cb * 8 + (l15 >> 1), part = lane & 1; const float cr = __shfl(cfr, pb), ci = __shfl(cfi, pb);
;             bf16x8 f = (bf16x8){0, 0, 0, 0, 0, 0, 0, 0};
;             if (lq < 2) { const float* br = pp->in[7] + (pg * 64 + pb) * 16 + lq * 8; const float* bi = pp->in[8] + (pg * 64 + pb) * 16 + lq * 8;
;                 const f32x4 br0 = *(const f32x4*)br, br1 = *(const f32x4*)(br + 4), bi0 = *(const f32x4*)bi, bi1 = *(const f32x4*)(bi + 4);
;                 float vv[8];
; #pragma unroll
;                 for (int j = 0; j < 8; ++j) { const float bre = j < 4 ? br0[j & 3] : br1[j & 3], bim = j < 4 ? bi0[j & 3] : bi1[j & 3]; vv[j] = part ? (cr * bim + ci * bre) : (cr * bre - ci * bim); }
;                 const unsigned w0 = cvt_pk_bf16(vv[0], vv[1]), w1 = cvt_pk_bf16(vv[2], vv[3]), w2 = cvt_pk_bf16(vv[4], vv[5]), w3 = cvt_pk_bf16(vv[6], vv[7]);
;                 f[0] = (short)(w0 & 0xffff); f[1] = (short)(w0 >> 16); f[2] = (short)(w1 & 0xffff); f[3] = (short)(w1 >> 16); f[4] = (short)(w2 & 0xffff); f[5] = (short)(w2 >> 16); f[6] = (short)(w3 & 0xffff); f[7] = (short)(w3 >> 16); }
	v_fmac_f64_e32 v[4:5], v[10:11], v[12:13]
	v_mul_f64 v[10:11], v[2:3], s[28:29]
	s_mov_b32 s28, 0x1ac5701b
	v_writelane_b32 v238, s61, 20
	s_mov_b32 s29, 0x3f6ac570
	v_mul_f64 v[12:13], v[10:11], v[16:17]
	v_fmac_f64_e32 v[0:1], v[10:11], v[16:17]
	v_mul_f64 v[10:11], v[2:3], s[28:29]
	v_readlane_b32 s28, v238, 21
	v_readlane_b32 s29, v238, 22
	s_mov_b32 s61, s29
	v_writelane_b32 v238, s28, 21
	v_mul_f64 v[16:17], v[10:11], v[14:15]
	v_fmac_f64_e32 v[4:5], v[10:11], v[14:15]
	v_writelane_b32 v238, s29, 22
	s_mov_b32 s28, 0x308158ed
	v_mul_f64 v[10:11], v[2:3], s[60:61]
	s_mov_b32 s29, 0x3f658ed2
	v_mul_f64 v[14:15], v[10:11], v[12:13]
	v_fmac_f64_e32 v[0:1], v[10:11], v[12:13]
	v_mul_f64 v[10:11], v[2:3], s[28:29]
	s_mov_b32 s28, 0xb51f5e1a
	s_mov_b32 s29, 0x3f603091
	v_mul_f64 v[12:13], v[10:11], v[16:17]
	v_fmac_f64_e32 v[4:5], v[10:11], v[16:17]
	v_mul_f64 v[10:11], v[2:3], s[28:29]
	s_mov_b32 s28, 0x4046ed29
	s_mov_b32 s29, 0x3f61bb4a
	v_mul_f64 v[16:17], v[10:11], v[14:15]
	v_fmac_f64_e32 v[0:1], v[10:11], v[14:15]
	v_mul_f64 v[10:11], v[2:3], s[28:29]
	s_mov_b32 s28, 0xb4e81b4f
	s_mov_b32 s29, 0x3f5b4e81
	v_mul_f64 v[14:15], v[10:11], v[12:13]
	v_fmac_f64_e32 v[4:5], v[10:11], v[12:13]
	v_mul_f64 v[10:11], v[2:3], s[28:29]
	s_mov_b32 s28, 0x76b981db
	s_mov_b32 s29, 0x3f5dae60
	v_mul_f64 v[12:13], v[10:11], v[16:17]
	v_fmac_f64_e32 v[0:1], v[10:11], v[16:17]
	v_mul_f64 v[10:11], v[2:3], s[28:29]
	s_mov_b32 s28, 0xc201756d
	s_mov_b32 s29, 0x3f5756ca
	v_mul_f64 v[16:17], v[10:11], v[14:15]
	v_fmac_f64_e32 v[4:5], v[10:11], v[14:15]
	v_mul_f64 v[10:11], v[2:3], s[28:29]
	s_mov_b32 s28, 0x7f9b2ce6
	s_mov_b32 s29, 0x3f5934c6
	v_mul_f64 v[14:15], v[10:11], v[12:13]
	v_fmac_f64_e32 v[0:1], v[10:11], v[12:13]
	v_mul_f64 v[10:11], v[2:3], s[28:29]
	s_mov_b32 s28, 0x25d51f87
	s_mov_b32 s29, 0x3f542d66
	v_mul_f64 v[12:13], v[10:11], v[16:17]
	v_fmac_f64_e32 v[4:5], v[10:11], v[16:17]
	v_mul_f64 v[10:11], v[2:3], s[28:29]
	s_mov_b32 s28, 0x6b015ac0
	v_fmac_f64_e32 v[0:1], v[10:11], v[14:15]
	s_mov_b32 s29, 0x3f55ac05
	v_mul_f64 v[2:3], v[2:3], s[28:29]
	v_cvt_f32_f64_e32 v0, v[0:1]
	v_mul_f32_e32 v1, v6, v8
	v_fmac_f64_e32 v[4:5], v[2:3], v[12:13]
	v_mul_f32_e32 v2, 0x3fb8aa3b, v1
	v_cvt_f32_f64_e32 v25, v[4:5]
	v_fma_f32 v3, v1, s5, -v2
	v_rndne_f32_e32 v4, v2
	v_fmac_f32_e32 v3, 0x32a5705f, v1
	v_sub_f32_e32 v2, v2, v4
	v_add_f32_e32 v2, v2, v3
	v_exp_f32_e32 v2, v2
	v_cvt_i32_f32_e32 v3, v4
	v_cmp_ngt_f32_e32 vcc, s36, v1
	v_ldexp_f32 v2, v2, v3
	s_nop 0
	v_cndmask_b32_e32 v2, 0, v2, vcc
	v_cmp_nlt_f32_e32 vcc, s88, v1
	s_nop 1
	v_cndmask_b32_e32 v27, v205, v2, vcc
	v_mul_f32_e32 v107, v27, v0
	v_mul_f32_e32 v0, v7, v7
	v_fmac_f32_e32 v0, v6, v6
	v_div_scale_f32 v1, s[28:29], v0, v0, 1.0
	v_rcp_f32_e32 v2, v1
	s_nop 0
	v_fma_f32 v3, -v1, v2, 1.0
	v_fmac_f32_e32 v2, v3, v2
	v_div_scale_f32 v3, vcc, 1.0, v0, 1.0
	v_mul_f32_e32 v4, v3, v2
	v_fma_f32 v5, -v1, v4, v3
	v_fmac_f32_e32 v4, v5, v2
	v_fma_f32 v1, -v1, v4, v3
	v_div_fmas_f32 v1, v1, v2, v4
	v_div_fixup_f32 v0, v1, v0, 1.0
	v_fma_f32 v1, v27, v25, -1.0
	v_mul_f32_e32 v2, v7, v107
	v_fmac_f32_e32 v2, v6, v1
	v_mul_f32_e32 v1, v7, v1
	v_fma_f32 v1, v6, v107, -v1
	v_mul_f32_e32 v28, v0, v2
	v_mul_f32_e32 v29, v0, v1
	ds_bpermute_b32 v2, v71, v28
	ds_bpermute_b32 v8, v71, v29
	v_mov_b32_e32 v0, 0
	v_mov_b32_e32 v4, 0
	v_mov_b32_e32 v5, 0
	v_mov_b32_e32 v6, 0
	v_mov_b32_e32 v7, 0
	s_and_saveexec_b64 s[88:89], s[42:43]
	s_cbranch_execz .LBB0_347
	s_load_dwordx4 s[60:63], s[0:1], 0x38
	v_mov_b32_e32 v5, s67
	v_or_b32_e32 v4, s66, v72
	v_lshlrev_b64 v[4:5], 6, v[4:5]
	s_waitcnt lgkmcnt(0)
	v_lshl_add_u64 v[6:7], s[60:61], 0, v[4:5]
	v_lshl_add_u64 v[4:5], s[62:63], 0, v[4:5]
	v_lshl_add_u64 v[10:11], v[6:7], 0, v[178:179]
	v_lshl_add_u64 v[18:19], v[4:5], 0, v[178:179]
	global_load_dwordx4 v[4:7], v[10:11], off offset:16
	s_nop 0
	global_load_dwordx4 v[10:13], v[10:11], off
	s_nop 0
	global_load_dwordx4 v[14:17], v[18:19], off offset:16
	s_nop 0
	global_load_dwordx4 v[18:21], v[18:19], off
	s_waitcnt vmcnt(0)
	v_pk_mul_f32 v[22:23], v[18:19], v[2:3] op_sel_hi:[1,0]
	v_pk_mul_f32 v[18:19], v[18:19], v[8:9] op_sel_hi:[1,0]
	v_pk_fma_f32 v[22:23], v[10:11], v[8:9], v[22:23] op_sel_hi:[1,0,1]
	v_pk_fma_f32 v[10:11], v[10:11], v[2:3], v[18:19] op_sel_hi:[1,0,1] neg_lo:[0,0,1] neg_hi:[0,0,1]
	v_pk_mul_f32 v[18:19], v[20:21], v[8:9] op_sel_hi:[1,0]
	v_cndmask_b32_e64 v1, v23, v11, s[44:45]
	v_cndmask_b32_e64 v22, v22, v10, s[44:45]
	v_pk_mul_f32 v[10:11], v[20:21], v[2:3] op_sel_hi:[1,0]
	s_nop 0
	v_pk_fma_f32 v[10:11], v[12:13], v[8:9], v[10:11] op_sel_hi:[1,0,1]
	v_pk_fma_f32 v[12:13], v[12:13], v[2:3], v[18:19] op_sel_hi:[1,0,1] neg_lo:[0,0,1] neg_hi:[0,0,1]
	s_nop 0
	v_cndmask_b32_e64 v18, v11, v13, s[44:45]
	v_cndmask_b32_e64 v19, v10, v12, s[44:45]
	v_pk_mul_f32 v[10:11], v[14:15], v[2:3] op_sel_hi:[1,0]
	v_pk_mul_f32 v[12:13], v[14:15], v[8:9] op_sel_hi:[1,0]
	v_pk_fma_f32 v[10:11], v[4:5], v[8:9], v[10:11] op_sel_hi:[1,0,1]
	v_pk_fma_f32 v[4:5], v[4:5], v[2:3], v[12:13] op_sel_hi:[1,0,1] neg_lo:[0,0,1] neg_hi:[0,0,1]
	s_nop 0
	v_cndmask_b32_e64 v11, v11, v5, s[44:45]
	v_cndmask_b32_e64 v10, v10, v4, s[44:45]
	v_pk_mul_f32 v[4:5], v[16:17], v[2:3] op_sel_hi:[1,0]
	s_nop 0
	v_pk_fma_f32 v[4:5], v[6:7], v[8:9], v[4:5] op_sel_hi:[1,0,1]
	v_pk_mul_f32 v[8:9], v[16:17], v[8:9] op_sel_hi:[1,0]
	s_nop 0
	v_pk_fma_f32 v[2:3], v[6:7], v[2:3], v[8:9] op_sel_hi:[1,0,1] neg_lo:[0,0,1] neg_hi:[0,0,1]
	v_cvt_pk_bf16_f32 v6, v10, v11
	v_cndmask_b32_e64 v3, v5, v3, s[44:45]
	v_cndmask_b32_e64 v2, v4, v2, s[44:45]
	v_cvt_pk_bf16_f32 v4, v22, v1
	v_cvt_pk_bf16_f32 v5, v19, v18
	v_cvt_pk_bf16_f32 v7, v2, v3
